# sc1 stores in GEMM epilogues; closed-form unit count and pipelined rtab loads in chunk GEMM prologue
# speedup vs baseline: 1.0072x; 1.0072x over previous
.LBB0_132:
	v_cvt_pk_bf16_f32 v126, v126, v127
	v_cvt_pk_bf16_f32 v127, v128, v129
	v_cvt_pk_bf16_f32 v128, v122, v123
	v_add_u32_e32 v122, 0x80, v148
	v_cndmask_b32_e64 v123, 0, 1, s[30:31]
	v_ashrrev_i32_e32 v122, 5, v122
	v_cvt_pk_bf16_f32 v129, v124, v125
	v_cmp_ne_u32_e64 s[4:5], 1, v123
	s_andn2_b64 vcc, exec, s[30:31]
	v_ashrrev_i32_e32 v123, 31, v122
	global_store_dwordx4 v[156:157], v[126:129], off sc1
	s_cbranch_vccnz .LBB0_181
	v_lshlrev_b64 v[124:125], 17, v[122:123]
	v_lshl_add_u64 v[124:125], s[16:17], 0, v[124:125]
	v_lshl_add_u64 v[124:125], v[124:125], 0, v[154:155]
	v_lshl_add_u64 v[124:125], v[124:125], 0, v[138:139]
	s_cbranch_execnz .LBB0_135

.LBB0_135:
	v_cvt_pk_bf16_f32 v118, v118, v119
	v_cvt_pk_bf16_f32 v119, v120, v121
	v_cvt_pk_bf16_f32 v120, v114, v115
	v_or_b32_e32 v114, 16, v150
	v_ashrrev_i32_e32 v115, 31, v114
	v_cvt_pk_bf16_f32 v121, v116, v117
	s_and_b64 vcc, exec, s[4:5]
	v_lshlrev_b64 v[116:117], 6, v[114:115]
	global_store_dwordx4 v[124:125], v[118:121], off sc1
	s_cbranch_vccnz .LBB0_182
	s_nop 0
	v_lshlrev_b64 v[118:119], 17, v[152:153]
	v_lshl_add_u64 v[118:119], s[16:17], 0, v[118:119]
	v_lshl_add_u64 v[118:119], v[118:119], 0, v[116:117]
	v_lshl_add_u64 v[118:119], v[118:119], 0, v[138:139]
	s_cbranch_execnz .LBB0_138

.LBB0_138:
	v_cvt_pk_bf16_f32 v110, v110, v111
	v_cvt_pk_bf16_f32 v111, v112, v113
	v_cvt_pk_bf16_f32 v112, v106, v107
	v_cvt_pk_bf16_f32 v113, v108, v109
	s_and_b64 vcc, exec, s[4:5]
	global_store_dwordx4 v[118:119], v[110:113], off sc1
	s_cbranch_vccnz .LBB0_183
	v_lshlrev_b64 v[106:107], 17, v[122:123]
	v_lshl_add_u64 v[106:107], s[16:17], 0, v[106:107]
	v_lshl_add_u64 v[106:107], v[106:107], 0, v[116:117]
	v_lshl_add_u64 v[106:107], v[106:107], 0, v[138:139]
	s_cbranch_execnz .LBB0_141

.LBB0_141:
	v_cvt_pk_bf16_f32 v102, v102, v103
	v_cvt_pk_bf16_f32 v103, v104, v105
	v_cvt_pk_bf16_f32 v104, v98, v99
	v_or_b32_e32 v98, 32, v150
	v_ashrrev_i32_e32 v99, 31, v98
	v_cvt_pk_bf16_f32 v105, v100, v101
	s_and_b64 vcc, exec, s[4:5]
	v_lshlrev_b64 v[100:101], 6, v[98:99]
	global_store_dwordx4 v[106:107], v[102:105], off sc1
	s_cbranch_vccnz .LBB0_184
	s_nop 0
	v_lshlrev_b64 v[102:103], 17, v[152:153]
	v_lshl_add_u64 v[102:103], s[16:17], 0, v[102:103]
	v_lshl_add_u64 v[102:103], v[102:103], 0, v[100:101]
	v_lshl_add_u64 v[102:103], v[102:103], 0, v[138:139]
	s_cbranch_execnz .LBB0_144

.LBB0_144:
	v_cvt_pk_bf16_f32 v94, v94, v95
	v_cvt_pk_bf16_f32 v95, v96, v97
	v_cvt_pk_bf16_f32 v96, v90, v91
	v_cvt_pk_bf16_f32 v97, v92, v93
	s_and_b64 vcc, exec, s[4:5]
	global_store_dwordx4 v[102:103], v[94:97], off sc1
	s_cbranch_vccnz .LBB0_185
	v_lshlrev_b64 v[90:91], 17, v[122:123]
	v_lshl_add_u64 v[90:91], s[16:17], 0, v[90:91]
	v_lshl_add_u64 v[90:91], v[90:91], 0, v[100:101]
	v_lshl_add_u64 v[90:91], v[90:91], 0, v[138:139]
	s_cbranch_execnz .LBB0_147

.LBB0_147:
	v_cvt_pk_bf16_f32 v86, v86, v87
	v_cvt_pk_bf16_f32 v87, v88, v89
	v_cvt_pk_bf16_f32 v88, v82, v83
	v_or_b32_e32 v82, 48, v150
	v_ashrrev_i32_e32 v83, 31, v82
	v_cvt_pk_bf16_f32 v89, v84, v85
	s_and_b64 vcc, exec, s[4:5]
	v_lshlrev_b64 v[84:85], 6, v[82:83]
	global_store_dwordx4 v[90:91], v[86:89], off sc1
	s_cbranch_vccnz .LBB0_186
	s_nop 0
	v_lshlrev_b64 v[86:87], 17, v[152:153]
	v_lshl_add_u64 v[86:87], s[16:17], 0, v[86:87]
	v_lshl_add_u64 v[86:87], v[86:87], 0, v[84:85]
	v_lshl_add_u64 v[86:87], v[86:87], 0, v[138:139]
	s_cbranch_execnz .LBB0_150

.LBB0_150:
	v_cvt_pk_bf16_f32 v78, v78, v79
	v_cvt_pk_bf16_f32 v79, v80, v81
	v_cvt_pk_bf16_f32 v80, v74, v75
	v_cvt_pk_bf16_f32 v81, v76, v77
	s_and_b64 vcc, exec, s[4:5]
	global_store_dwordx4 v[86:87], v[78:81], off sc1
	s_cbranch_vccnz .LBB0_187
	v_lshlrev_b64 v[74:75], 17, v[122:123]
	v_lshl_add_u64 v[74:75], s[16:17], 0, v[74:75]
	v_lshl_add_u64 v[74:75], v[74:75], 0, v[84:85]
	v_lshl_add_u64 v[74:75], v[74:75], 0, v[138:139]
	s_cbranch_execnz .LBB0_153

.LBB0_153:
	v_cvt_pk_bf16_f32 v70, v70, v71
	v_cvt_pk_bf16_f32 v71, v72, v73
	v_cvt_pk_bf16_f32 v72, v66, v67
	v_add_u32_e32 v66, 0x80, v150
	v_ashrrev_i32_e32 v67, 31, v66
	v_cvt_pk_bf16_f32 v73, v68, v69
	s_and_b64 vcc, exec, s[4:5]
	v_lshlrev_b64 v[68:69], 6, v[66:67]
	global_store_dwordx4 v[74:75], v[70:73], off sc1
	s_cbranch_vccnz .LBB0_188
	s_nop 0
	v_lshlrev_b64 v[70:71], 17, v[152:153]
	v_lshl_add_u64 v[70:71], s[16:17], 0, v[70:71]
	v_lshl_add_u64 v[70:71], v[70:71], 0, v[68:69]
	v_lshl_add_u64 v[70:71], v[70:71], 0, v[138:139]
	s_cbranch_execnz .LBB0_156

.LBB0_156:
	v_cvt_pk_bf16_f32 v62, v62, v63
	v_cvt_pk_bf16_f32 v63, v64, v65
	v_cvt_pk_bf16_f32 v64, v58, v59
	v_cvt_pk_bf16_f32 v65, v60, v61
	s_and_b64 vcc, exec, s[4:5]
	global_store_dwordx4 v[70:71], v[62:65], off sc1
	s_cbranch_vccnz .LBB0_189
	v_lshlrev_b64 v[58:59], 17, v[122:123]
	v_lshl_add_u64 v[58:59], s[16:17], 0, v[58:59]
	v_lshl_add_u64 v[58:59], v[58:59], 0, v[68:69]
	v_lshl_add_u64 v[58:59], v[58:59], 0, v[138:139]
	s_cbranch_execnz .LBB0_159

.LBB0_159:
	v_cvt_pk_bf16_f32 v54, v54, v55
	v_cvt_pk_bf16_f32 v55, v56, v57
	v_cvt_pk_bf16_f32 v56, v50, v51
	v_add_u32_e32 v50, 0x90, v150
	v_ashrrev_i32_e32 v51, 31, v50
	v_cvt_pk_bf16_f32 v57, v52, v53
	s_and_b64 vcc, exec, s[4:5]
	v_lshlrev_b64 v[52:53], 6, v[50:51]
	global_store_dwordx4 v[58:59], v[54:57], off sc1
	s_cbranch_vccnz .LBB0_190
	s_nop 0
	v_lshlrev_b64 v[54:55], 17, v[152:153]
	v_lshl_add_u64 v[54:55], s[16:17], 0, v[54:55]
	v_lshl_add_u64 v[54:55], v[54:55], 0, v[52:53]
	v_lshl_add_u64 v[54:55], v[54:55], 0, v[138:139]
	s_cbranch_execnz .LBB0_162

.LBB0_162:
	v_cvt_pk_bf16_f32 v46, v46, v47
	v_cvt_pk_bf16_f32 v47, v48, v49
	v_cvt_pk_bf16_f32 v48, v42, v43
	v_cvt_pk_bf16_f32 v49, v44, v45
	s_and_b64 vcc, exec, s[4:5]
	global_store_dwordx4 v[54:55], v[46:49], off sc1
	s_cbranch_vccnz .LBB0_191
	v_lshlrev_b64 v[42:43], 17, v[122:123]
	v_lshl_add_u64 v[42:43], s[16:17], 0, v[42:43]
	v_lshl_add_u64 v[42:43], v[42:43], 0, v[52:53]
	v_lshl_add_u64 v[42:43], v[42:43], 0, v[138:139]
	s_cbranch_execnz .LBB0_165

.LBB0_165:
	v_cvt_pk_bf16_f32 v38, v38, v39
	v_cvt_pk_bf16_f32 v39, v40, v41
	v_cvt_pk_bf16_f32 v40, v34, v35
	v_add_u32_e32 v34, 0xa0, v150
	v_ashrrev_i32_e32 v35, 31, v34
	v_cvt_pk_bf16_f32 v41, v36, v37
	s_and_b64 vcc, exec, s[4:5]
	v_lshlrev_b64 v[36:37], 6, v[34:35]
	global_store_dwordx4 v[42:43], v[38:41], off sc1
	s_cbranch_vccnz .LBB0_192
	s_nop 0
	v_lshlrev_b64 v[38:39], 17, v[152:153]
	v_lshl_add_u64 v[38:39], s[16:17], 0, v[38:39]
	v_lshl_add_u64 v[38:39], v[38:39], 0, v[36:37]
	v_lshl_add_u64 v[38:39], v[38:39], 0, v[138:139]
	s_cbranch_execnz .LBB0_168

.LBB0_168:
	v_cvt_pk_bf16_f32 v30, v30, v31
	v_cvt_pk_bf16_f32 v31, v32, v33
	v_cvt_pk_bf16_f32 v32, v26, v27
	v_cvt_pk_bf16_f32 v33, v28, v29
	s_and_b64 vcc, exec, s[4:5]
	global_store_dwordx4 v[38:39], v[30:33], off sc1
	s_cbranch_vccnz .LBB0_193
	v_lshlrev_b64 v[26:27], 17, v[122:123]
	v_lshl_add_u64 v[26:27], s[16:17], 0, v[26:27]
	v_lshl_add_u64 v[26:27], v[26:27], 0, v[36:37]
	v_lshl_add_u64 v[26:27], v[26:27], 0, v[138:139]
	s_cbranch_execnz .LBB0_171

.LBB0_171:
	v_cvt_pk_bf16_f32 v22, v22, v23
	v_cvt_pk_bf16_f32 v23, v24, v25
	v_cvt_pk_bf16_f32 v24, v18, v19
	v_add_u32_e32 v18, 0xb0, v150
	v_ashrrev_i32_e32 v19, 31, v18
	v_cvt_pk_bf16_f32 v25, v20, v21
	s_and_b64 vcc, exec, s[4:5]
	v_lshlrev_b64 v[20:21], 6, v[18:19]
	global_store_dwordx4 v[26:27], v[22:25], off sc1
	s_cbranch_vccnz .LBB0_194
	s_nop 0
	v_lshlrev_b64 v[22:23], 17, v[152:153]
	v_lshl_add_u64 v[22:23], s[16:17], 0, v[22:23]
	v_lshl_add_u64 v[22:23], v[22:23], 0, v[20:21]
	v_lshl_add_u64 v[22:23], v[22:23], 0, v[138:139]
	s_cbranch_execnz .LBB0_174

.LBB0_174:
	v_cvt_pk_bf16_f32 v14, v14, v15
	v_cvt_pk_bf16_f32 v15, v16, v17
	v_cvt_pk_bf16_f32 v16, v10, v11
	v_cvt_pk_bf16_f32 v17, v12, v13
	s_and_b64 vcc, exec, s[4:5]
	global_store_dwordx4 v[22:23], v[14:17], off sc1
	s_cbranch_vccnz .LBB0_195
	v_lshlrev_b64 v[10:11], 17, v[122:123]
	v_lshl_add_u64 v[10:11], s[16:17], 0, v[10:11]
	v_lshl_add_u64 v[10:11], v[10:11], 0, v[20:21]
	v_lshl_add_u64 v[10:11], v[10:11], 0, v[138:139]
	s_cbranch_execnz .LBB0_177

.LBB0_177:
	v_cvt_pk_bf16_f32 v6, v6, v7
	v_cvt_pk_bf16_f32 v7, v8, v9
	v_cvt_pk_bf16_f32 v8, v2, v3
	v_cvt_pk_bf16_f32 v9, v4, v5
	s_andn2_b64 vcc, exec, s[28:29]
	s_mov_b64 s[4:5], -1
	global_store_dwordx4 v[10:11], v[6:9], off sc1
	s_cbranch_vccnz .LBB0_120
	s_andn2_b64 vcc, exec, s[10:11]
	s_cbranch_vccnz .LBB0_119
	s_barrier
	s_branch .LBB0_119

.LBB0_903:
	s_lshl_b32 s96, s95, 1
	s_add_i32 s4, s96, 7
	s_cmp_le_i32 s79, s4
	s_cselect_b64 s[0:1], -1, 0
	s_cmp_lt_i32 s4, s78
	s_cselect_b64 s[4:5], -1, 0
	s_and_b64 s[0:1], s[0:1], s[4:5]
	s_andn2_b64 vcc, exec, s[0:1]
	s_cbranch_vccnz .LBB0_1049
	s_mov_b64 s[4:5], s[92:93]
	v_mbcnt_lo_u32_b32 v0, -1, 0
	v_mbcnt_hi_u32_b32 v0, -1, v0
	s_mov_b32 s14, s95
	v_add_u32_e32 v2, s37, v0
	s_cmp_lt_i32 s14, 2
	s_cselect_b64 s[12:13], -1, 0
	s_load_dwordx2 s[8:9], s[4:5], 0x70
	s_and_b64 s[4:5], s[12:13], exec
	s_cselect_b32 s58, 11, 10
	s_lshl_b32 s4, 1, s58
	s_add_i32 s60, s58, -8
	s_lshr_b32 s59, s4, 8
	s_lshl_b32 s5, 3, s60
	s_lshr_b32 s6, s4, 7
	s_cmp_gt_i32 s14, 1
	s_cselect_b32 s30, s5, s6
	s_lshl_b32 s44, s30, 6
	s_lshr_b32 s46, s4, 2
	s_mov_b32 s45, s57
	s_sub_u32 s15, 0, s44
	s_mov_b32 s47, s57
	s_subb_u32 s19, 0, 0
	s_mov_b32 s18, 0
	v_mov_b64_e32 v[0:1], s[44:45]
	s_mov_b64 s[6:7], s[2:3]
	s_cmp_lg_u32 s52, 0x100
	s_cbranch_scc1 .LBB0_907
	s_add_i32 s18, s44, s46
	s_sub_i32 s18, s18, s2
	s_add_i32 s18, s18, 0xff
	s_lshr_b32 s18, s18, 8
	s_cmp_gt_u32 s18, 15
	s_cbranch_scc1 .Lnu_generic
	s_mov_b64 s[4:5], 0
	s_branch .LBB0_917
.Lnu_generic:
	s_mov_b32 s18, 0
	s_branch .LBB0_907

.LBB0_917:
	s_min_i32 s6, s14, 2
	s_lshl_b32 s53, s6, 1
	s_sub_i32 s61, 6, s53
	s_mov_b32 s28, 0
	s_and_b64 vcc, exec, s[4:5]
	s_cbranch_vccnz .LBB0_935
	s_lshl_b32 s22, s18, 8
	v_cmp_gt_i32_e32 vcc, s22, v2
	s_and_saveexec_b64 s[6:7], vcc
	s_cbranch_execz .LBB0_934
	v_and_b32_e32 v0, 15, v2
	s_waitcnt lgkmcnt(0)
	s_add_u32 s10, s8, 0x1000000
	v_subrev_co_u32_e32 v1, vcc, 4, v0
	v_cmp_gt_u32_e64 s[40:41], 12, v0
	s_addc_u32 s11, s9, 0
	s_lshl_b32 s14, -1, s61
	v_cndmask_b32_e64 v1, v0, v1, s[40:41]
	v_add_u32_e32 v4, 4, v0
	v_cmp_gt_u32_e64 s[40:41], 8, v0
	s_not_b32 s23, s14
	v_readlane_b32 s14, v253, 59
	v_cndmask_b32_e64 v1, v1, v4, s[40:41]
	v_and_b32_e32 v3, 0xff, v2
	v_cndmask_b32_e32 v4, v1, v0, vcc
	v_lshl_add_u32 v5, v2, 2, s14
	s_mov_b64 s[14:15], 0
	s_cmp_eq_u32 s18, 6
	s_cbranch_scc1 .Lrt_fast
	s_cmp_eq_u32 s18, 4
	s_cbranch_scc0 .LBB0_921

.Lrt0_920:
	s_or_b64 exec, exec, s[18:19]
	v_ashrrev_i32_e32 v1, 31, v0
	v_lshl_add_u64 v[0:1], v[0:1], 4, s[10:11]
	global_load_dwordx4 v[200:203], v[0:1], off
	v_add_u32_e32 v2, 0x200, v2
	v_ashrrev_i32_e32 v6, 8, v2
	v_mov_b64_e32 v[0:1], s[2:3]
	v_mad_i64_i32 v[0:1], s[18:19], v6, s52, v[0:1]
	v_cmp_gt_i64_e64 s[20:21], s[44:45], v[0:1]
	v_cmp_le_i64_e32 vcc, s[44:45], v[0:1]
	v_mov_b32_e32 v7, 64
	v_mov_b32_e32 v6, 0
	v_mov_b32_e32 v8, s30
	s_and_saveexec_b64 s[18:19], vcc
	v_subrev_co_u32_e32 v0, vcc, s44, v0
	s_andn2_b64 s[20:21], s[20:21], exec
	s_nop 0
	v_subbrev_co_u32_e32 v1, vcc, 0, v1, vcc
	v_cmp_gt_i64_e32 vcc, s[46:47], v[0:1]
	s_and_b64 s[24:25], vcc, exec
	v_mov_b32_e32 v8, 64
	v_mov_b32_e32 v6, 1
	v_mov_b32_e32 v7, s59
	s_or_b64 s[20:21], s[20:21], s[24:25]
	s_or_b64 exec, exec, s[18:19]
	s_and_saveexec_b64 s[18:19], s[20:21]
	s_cbranch_execz .Lrt1_929
	v_mul_i32_i24_e32 v1, v7, v8
	v_lshrrev_b32_e32 v11, 3, v1
	v_and_b32_e32 v12, 7, v1
	v_ashrrev_i32_e32 v1, 31, v0
	v_lshrrev_b32_e32 v1, 29, v1
	v_add_u32_e32 v1, v0, v1
	v_and_b32_e32 v9, -8, v1
	v_sub_u32_e32 v9, v0, v9
	v_cmp_ge_i32_e32 vcc, v9, v12
	v_add_u32_e32 v10, 1, v11
	s_and_saveexec_b64 s[20:21], vcc
	s_xor_b64 s[20:21], exec, s[20:21]
	v_sub_u32_e32 v0, v9, v12
	v_mul_lo_u32 v0, v0, v11
	v_mad_u32_u24 v0, v10, v12, v0
	s_andn2_saveexec_b64 s[20:21], s[20:21]
	v_mul_lo_u32 v0, v9, v10
	s_or_b64 exec, exec, s[20:21]
	v_ashrrev_i32_e32 v1, 3, v1
	v_add_u32_e32 v0, v0, v1
	v_lshlrev_b32_e32 v1, 3, v8
	v_sub_u32_e32 v10, 0, v1
	v_max_i32_e32 v10, v1, v10
	v_cvt_f32_u32_e32 v11, v10
	v_sub_u32_e32 v12, 0, v10
	v_sub_u32_e32 v9, 0, v0
	v_max_i32_e32 v9, v0, v9
	v_rcp_iflag_f32_e32 v11, v11
	v_xor_b32_e32 v8, v0, v1
	v_ashrrev_i32_e32 v8, 31, v8
	v_mov_b32_e32 v188, v6
	v_mul_f32_e32 v11, 0x4f7ffffe, v11
	v_cvt_u32_f32_e32 v11, v11
	v_mul_lo_u32 v12, v12, v11
	v_mul_hi_u32 v12, v11, v12
	v_add_u32_e32 v11, v11, v12
	v_mul_hi_u32 v11, v9, v11
	v_mul_lo_u32 v12, v11, v10
	v_sub_u32_e32 v9, v9, v12
	v_cmp_ge_u32_e32 vcc, v9, v10
	v_add_u32_e32 v12, 1, v11
	s_nop 0
	v_cndmask_b32_e32 v11, v11, v12, vcc
	v_sub_u32_e32 v12, v9, v10
	v_cndmask_b32_e32 v9, v9, v12, vcc
	v_cmp_ge_u32_e32 vcc, v9, v10
	v_add_u32_e32 v9, 1, v11
	s_nop 0
	v_cndmask_b32_e32 v9, v11, v9, vcc
	v_xor_b32_e32 v9, v9, v8
	v_sub_u32_e32 v8, v9, v8
	v_lshlrev_b32_e32 v9, 3, v8
	v_sub_u32_e32 v7, v7, v9
	v_min_i32_e32 v7, 8, v7
	v_sub_u32_e32 v10, 0, v7
	v_max_i32_e32 v10, v7, v10
	v_cvt_f32_u32_e32 v11, v10
	v_mul_lo_u32 v1, v8, v1
	v_sub_u32_e32 v12, 0, v10
	v_sub_u32_e32 v0, v0, v1
	v_rcp_iflag_f32_e32 v11, v11
	v_sub_u32_e32 v8, 0, v0
	v_max_i32_e32 v8, v0, v8
	v_xor_b32_e32 v1, v0, v7
	v_mul_f32_e32 v11, 0x4f7ffffe, v11
	v_cvt_u32_f32_e32 v11, v11
	v_ashrrev_i32_e32 v1, 31, v1
	v_mul_lo_u32 v12, v12, v11
	v_mul_hi_u32 v12, v11, v12
	v_add_u32_e32 v11, v11, v12
	v_mul_hi_u32 v11, v8, v11
	v_mul_lo_u32 v12, v11, v10
	v_sub_u32_e32 v8, v8, v12
	v_cmp_ge_u32_e32 vcc, v8, v10
	v_add_u32_e32 v12, 1, v11
	s_nop 0
	v_cndmask_b32_e32 v11, v11, v12, vcc
	v_sub_u32_e32 v12, v8, v10
	v_cndmask_b32_e32 v8, v8, v12, vcc
	v_cmp_ge_u32_e32 vcc, v8, v10
	v_add_u32_e32 v8, 1, v11
	s_nop 0
	v_cndmask_b32_e32 v8, v11, v8, vcc
	v_xor_b32_e32 v8, v8, v1
	v_sub_u32_e32 v189, v8, v1
	v_mul_lo_u32 v1, v189, v7
	v_sub_u32_e32 v0, v0, v1
	v_add_u32_e32 v190, v0, v9

.Lrt1_920:
	s_or_b64 exec, exec, s[18:19]
	v_ashrrev_i32_e32 v1, 31, v0
	v_lshl_add_u64 v[0:1], v[0:1], 4, s[10:11]
	global_load_dwordx4 v[204:207], v[0:1], off
	v_add_u32_e32 v2, 0x200, v2
	s_cmp_eq_u32 s22, 0x400
	s_cbranch_scc1 .Lrt_two
	v_ashrrev_i32_e32 v6, 8, v2
	v_mov_b64_e32 v[0:1], s[2:3]
	v_mad_i64_i32 v[0:1], s[18:19], v6, s52, v[0:1]
	v_cmp_gt_i64_e64 s[20:21], s[44:45], v[0:1]
	v_cmp_le_i64_e32 vcc, s[44:45], v[0:1]
	v_mov_b32_e32 v7, 64
	v_mov_b32_e32 v6, 0
	v_mov_b32_e32 v8, s30
	s_and_saveexec_b64 s[18:19], vcc
	v_subrev_co_u32_e32 v0, vcc, s44, v0
	s_andn2_b64 s[20:21], s[20:21], exec
	s_nop 0
	v_subbrev_co_u32_e32 v1, vcc, 0, v1, vcc
	v_cmp_gt_i64_e32 vcc, s[46:47], v[0:1]
	s_and_b64 s[24:25], vcc, exec
	v_mov_b32_e32 v8, 64
	v_mov_b32_e32 v6, 1
	v_mov_b32_e32 v7, s59
	s_or_b64 s[20:21], s[20:21], s[24:25]
	s_or_b64 exec, exec, s[18:19]
	s_and_saveexec_b64 s[18:19], s[20:21]
	s_cbranch_execz .Lrt2_929
	v_mul_i32_i24_e32 v1, v7, v8
	v_lshrrev_b32_e32 v11, 3, v1
	v_and_b32_e32 v12, 7, v1
	v_ashrrev_i32_e32 v1, 31, v0
	v_lshrrev_b32_e32 v1, 29, v1
	v_add_u32_e32 v1, v0, v1
	v_and_b32_e32 v9, -8, v1
	v_sub_u32_e32 v9, v0, v9
	v_cmp_ge_i32_e32 vcc, v9, v12
	v_add_u32_e32 v10, 1, v11
	s_and_saveexec_b64 s[20:21], vcc
	s_xor_b64 s[20:21], exec, s[20:21]
	v_sub_u32_e32 v0, v9, v12
	v_mul_lo_u32 v0, v0, v11
	v_mad_u32_u24 v0, v10, v12, v0
	s_andn2_saveexec_b64 s[20:21], s[20:21]
	v_mul_lo_u32 v0, v9, v10
	s_or_b64 exec, exec, s[20:21]
	v_ashrrev_i32_e32 v1, 3, v1
	v_add_u32_e32 v0, v0, v1
	v_lshlrev_b32_e32 v1, 3, v8
	v_sub_u32_e32 v10, 0, v1
	v_max_i32_e32 v10, v1, v10
	v_cvt_f32_u32_e32 v11, v10
	v_sub_u32_e32 v12, 0, v10
	v_sub_u32_e32 v9, 0, v0
	v_max_i32_e32 v9, v0, v9
	v_rcp_iflag_f32_e32 v11, v11
	v_xor_b32_e32 v8, v0, v1
	v_ashrrev_i32_e32 v8, 31, v8
	v_mov_b32_e32 v188, v6
	v_mul_f32_e32 v11, 0x4f7ffffe, v11
	v_cvt_u32_f32_e32 v11, v11
	v_mul_lo_u32 v12, v12, v11
	v_mul_hi_u32 v12, v11, v12
	v_add_u32_e32 v11, v11, v12
	v_mul_hi_u32 v11, v9, v11
	v_mul_lo_u32 v12, v11, v10
	v_sub_u32_e32 v9, v9, v12
	v_cmp_ge_u32_e32 vcc, v9, v10
	v_add_u32_e32 v12, 1, v11
	s_nop 0
	v_cndmask_b32_e32 v11, v11, v12, vcc
	v_sub_u32_e32 v12, v9, v10
	v_cndmask_b32_e32 v9, v9, v12, vcc
	v_cmp_ge_u32_e32 vcc, v9, v10
	v_add_u32_e32 v9, 1, v11
	s_nop 0
	v_cndmask_b32_e32 v9, v11, v9, vcc
	v_xor_b32_e32 v9, v9, v8
	v_sub_u32_e32 v8, v9, v8
	v_lshlrev_b32_e32 v9, 3, v8
	v_sub_u32_e32 v7, v7, v9
	v_min_i32_e32 v7, 8, v7
	v_sub_u32_e32 v10, 0, v7
	v_max_i32_e32 v10, v7, v10
	v_cvt_f32_u32_e32 v11, v10
	v_mul_lo_u32 v1, v8, v1
	v_sub_u32_e32 v12, 0, v10
	v_sub_u32_e32 v0, v0, v1
	v_rcp_iflag_f32_e32 v11, v11
	v_sub_u32_e32 v8, 0, v0
	v_max_i32_e32 v8, v0, v8
	v_xor_b32_e32 v1, v0, v7
	v_mul_f32_e32 v11, 0x4f7ffffe, v11
	v_cvt_u32_f32_e32 v11, v11
	v_ashrrev_i32_e32 v1, 31, v1
	v_mul_lo_u32 v12, v12, v11
	v_mul_hi_u32 v12, v11, v12
	v_add_u32_e32 v11, v11, v12
	v_mul_hi_u32 v11, v8, v11
	v_mul_lo_u32 v12, v11, v10
	v_sub_u32_e32 v8, v8, v12
	v_cmp_ge_u32_e32 vcc, v8, v10
	v_add_u32_e32 v12, 1, v11
	s_nop 0
	v_cndmask_b32_e32 v11, v11, v12, vcc
	v_sub_u32_e32 v12, v8, v10
	v_cndmask_b32_e32 v8, v8, v12, vcc
	v_cmp_ge_u32_e32 vcc, v8, v10
	v_add_u32_e32 v8, 1, v11
	s_nop 0
	v_cndmask_b32_e32 v8, v11, v8, vcc
	v_xor_b32_e32 v8, v8, v1
	v_sub_u32_e32 v189, v8, v1
	v_mul_lo_u32 v1, v189, v7
	v_sub_u32_e32 v0, v0, v1
	v_add_u32_e32 v190, v0, v9

.Lrt2_920:
	s_or_b64 exec, exec, s[18:19]
	v_ashrrev_i32_e32 v1, 31, v0
	v_lshl_add_u64 v[0:1], v[0:1], 4, s[10:11]
	global_load_dwordx4 v[208:211], v[0:1], off
	v_add_u32_e32 v2, 0x200, v2
	s_waitcnt vmcnt(2)
	v_add_f32_e32 v0, v201, v200
	v_add_f32_e32 v1, v202, v203
	v_add_f32_e32 v0, v0, v1
	v_fmamk_f32 v0, v0, 0x3a800000, v172
	v_cmp_gt_f32_e32 vcc, s33, v0
	v_mul_f32_e32 v1, 0x4b800000, v0
	s_nop 0
	v_cndmask_b32_e32 v0, v0, v1, vcc
	v_rsq_f32_e32 v0, v0
	s_nop 0
	v_mul_f32_e32 v1, 0x45800000, v0
	v_cndmask_b32_e32 v0, v0, v1, vcc
	ds_write_b32 v5, v0
	v_add_u32_e32 v5, 0x800, v5
	s_waitcnt vmcnt(1)
	v_add_f32_e32 v0, v205, v204
	v_add_f32_e32 v1, v206, v207
	v_add_f32_e32 v0, v0, v1
	v_fmamk_f32 v0, v0, 0x3a800000, v172
	v_cmp_gt_f32_e32 vcc, s33, v0
	v_mul_f32_e32 v1, 0x4b800000, v0
	s_nop 0
	v_cndmask_b32_e32 v0, v0, v1, vcc
	v_rsq_f32_e32 v0, v0
	s_nop 0
	v_mul_f32_e32 v1, 0x45800000, v0
	v_cndmask_b32_e32 v0, v0, v1, vcc
	ds_write_b32 v5, v0
	v_add_u32_e32 v5, 0x800, v5
	s_waitcnt vmcnt(0)
	v_add_f32_e32 v0, v209, v208
	v_add_f32_e32 v1, v210, v211
	v_add_f32_e32 v0, v0, v1
	v_fmamk_f32 v0, v0, 0x3a800000, v172
	v_cmp_gt_f32_e32 vcc, s33, v0
	v_mul_f32_e32 v1, 0x4b800000, v0
	s_nop 0
	v_cndmask_b32_e32 v0, v0, v1, vcc
	v_rsq_f32_e32 v0, v0
	s_nop 0
	v_mul_f32_e32 v1, 0x45800000, v0
	v_cndmask_b32_e32 v0, v0, v1, vcc
	ds_write_b32 v5, v0
	v_add_u32_e32 v5, 0x800, v5
	s_branch .LBB0_934
.Lrt_two:
	s_waitcnt vmcnt(1)
	v_add_f32_e32 v0, v201, v200
	v_add_f32_e32 v1, v202, v203
	v_add_f32_e32 v0, v0, v1
	v_fmamk_f32 v0, v0, 0x3a800000, v172
	v_cmp_gt_f32_e32 vcc, s33, v0
	v_mul_f32_e32 v1, 0x4b800000, v0
	s_nop 0
	v_cndmask_b32_e32 v0, v0, v1, vcc
	v_rsq_f32_e32 v0, v0
	s_nop 0
	v_mul_f32_e32 v1, 0x45800000, v0
	v_cndmask_b32_e32 v0, v0, v1, vcc
	ds_write_b32 v5, v0
	v_add_u32_e32 v5, 0x800, v5
	s_waitcnt vmcnt(0)
	v_add_f32_e32 v0, v205, v204
	v_add_f32_e32 v1, v206, v207
	v_add_f32_e32 v0, v0, v1
	v_fmamk_f32 v0, v0, 0x3a800000, v172
	v_cmp_gt_f32_e32 vcc, s33, v0
	v_mul_f32_e32 v1, 0x4b800000, v0
	s_nop 0
	v_cndmask_b32_e32 v0, v0, v1, vcc
	v_rsq_f32_e32 v0, v0
	s_nop 0
	v_mul_f32_e32 v1, 0x45800000, v0
	v_cndmask_b32_e32 v0, v0, v1, vcc
	ds_write_b32 v5, v0
	v_add_u32_e32 v5, 0x800, v5
	s_branch .LBB0_934
	s_branch .LBB0_921

.LBB0_973:
	s_lshl_b32 s12, s48, 8
	v_lshl_add_u32 v196, s84, 8, v156
	s_add_i32 s12, s12, s68
	v_ashrrev_i32_e32 v136, 5, v196
	v_and_or_b32 v150, v155, 15, s12
	v_ashrrev_i32_e32 v137, 31, v136
	v_ashrrev_i32_e32 v151, 31, v150
	v_lshlrev_b64 v[136:137], s58, v[136:137]
	v_lshl_add_u64 v[148:149], v[136:137], 0, v[150:151]
	v_and_b32_e32 v154, 24, v154
	v_lshlrev_b64 v[148:149], 6, v[148:149]
	v_lshl_add_u64 v[152:153], s[24:25], 0, v[148:149]
	v_lshlrev_b32_e32 v148, 1, v154
	v_mov_b32_e32 v149, v139
	v_lshl_add_u64 v[156:157], v[152:153], 0, v[148:149]
	s_waitcnt lgkmcnt(0)
	v_pk_mul_f32 v[152:153], v[124:125], v[128:129]
	v_pk_mul_f32 v[154:155], v[126:127], v[130:131]
	v_cvt_pk_bf16_f32 v152, v152, v153
	v_cvt_pk_bf16_f32 v153, v154, v155
	v_pk_mul_f32 v[154:155], v[120:121], v[132:133]
	v_pk_mul_f32 v[158:159], v[122:123], v[134:135]
	v_cvt_pk_bf16_f32 v154, v154, v155
	v_cvt_pk_bf16_f32 v155, v158, v159
	global_store_dwordx4 v[156:157], v[152:155], off sc1
	v_pk_mul_f32 v[156:157], v[110:111], v[130:131]
	v_pk_mul_f32 v[160:161], v[106:107], v[134:135]
	v_or_b32_e32 v152, 16, v150
	v_mov_b32_e32 v153, v151
	v_lshl_add_u64 v[154:155], v[136:137], 0, v[152:153]
	v_lshlrev_b64 v[154:155], 6, v[154:155]
	v_lshl_add_u64 v[154:155], s[24:25], 0, v[154:155]
	v_lshl_add_u64 v[158:159], v[154:155], 0, v[148:149]
	v_pk_mul_f32 v[154:155], v[108:109], v[128:129]
	v_pk_mul_f32 v[162:163], v[90:91], v[134:135]
	v_cvt_pk_bf16_f32 v154, v154, v155
	v_cvt_pk_bf16_f32 v155, v156, v157
	v_pk_mul_f32 v[156:157], v[104:105], v[132:133]
	v_pk_mul_f32 v[164:165], v[74:75], v[134:135]
	v_cvt_pk_bf16_f32 v156, v156, v157
	v_cvt_pk_bf16_f32 v157, v160, v161
	global_store_dwordx4 v[158:159], v[154:157], off sc1
	v_pk_mul_f32 v[158:159], v[94:95], v[130:131]
	v_pk_mul_f32 v[170:171], v[58:59], v[134:135]
	v_or_b32_e32 v154, 32, v150
	v_mov_b32_e32 v155, v151
	v_lshl_add_u64 v[156:157], v[136:137], 0, v[154:155]
	v_lshlrev_b64 v[156:157], 6, v[156:157]
	v_lshl_add_u64 v[156:157], s[24:25], 0, v[156:157]
	v_lshl_add_u64 v[160:161], v[156:157], 0, v[148:149]
	v_pk_mul_f32 v[156:157], v[92:93], v[128:129]
	s_mov_b64 s[12:13], 0x90
	v_cvt_pk_bf16_f32 v156, v156, v157
	v_cvt_pk_bf16_f32 v157, v158, v159
	v_pk_mul_f32 v[158:159], v[88:89], v[132:133]
	v_pk_mul_f32 v[198:199], v[42:43], v[134:135]
	v_cvt_pk_bf16_f32 v158, v158, v159
	v_cvt_pk_bf16_f32 v159, v162, v163
	global_store_dwordx4 v[160:161], v[156:159], off sc1
	v_pk_mul_f32 v[160:161], v[78:79], v[130:131]
	s_nop 0
	v_or_b32_e32 v156, 48, v150
	v_mov_b32_e32 v157, v151
	v_lshl_add_u64 v[158:159], v[136:137], 0, v[156:157]
	v_lshlrev_b64 v[158:159], 6, v[158:159]
	v_lshl_add_u64 v[158:159], s[24:25], 0, v[158:159]
	v_lshl_add_u64 v[162:163], v[158:159], 0, v[148:149]
	v_pk_mul_f32 v[158:159], v[76:77], v[128:129]
	s_nop 0
	v_cvt_pk_bf16_f32 v158, v158, v159
	v_cvt_pk_bf16_f32 v159, v160, v161
	v_pk_mul_f32 v[160:161], v[72:73], v[132:133]
	s_nop 0
	v_cvt_pk_bf16_f32 v160, v160, v161
	v_cvt_pk_bf16_f32 v161, v164, v165
	global_store_dwordx4 v[162:163], v[158:161], off sc1
	v_pk_mul_f32 v[162:163], v[62:63], v[130:131]
	s_nop 0
	v_lshl_add_u64 v[158:159], v[150:151], 0, s[16:17]
	v_lshl_add_u64 v[160:161], v[136:137], 0, v[158:159]
	v_lshlrev_b64 v[160:161], 6, v[160:161]
	v_lshl_add_u64 v[160:161], s[24:25], 0, v[160:161]
	v_lshl_add_u64 v[164:165], v[160:161], 0, v[148:149]
	v_pk_mul_f32 v[160:161], v[60:61], v[128:129]
	s_nop 0
	v_cvt_pk_bf16_f32 v160, v160, v161
	v_cvt_pk_bf16_f32 v161, v162, v163
	v_pk_mul_f32 v[162:163], v[56:57], v[132:133]
	s_nop 0
	v_cvt_pk_bf16_f32 v162, v162, v163
	v_cvt_pk_bf16_f32 v163, v170, v171
	global_store_dwordx4 v[164:165], v[160:163], off sc1
	v_pk_mul_f32 v[164:165], v[46:47], v[130:131]
	s_nop 0
	v_lshl_add_u64 v[160:161], v[150:151], 0, s[12:13]
	v_lshl_add_u64 v[162:163], v[136:137], 0, v[160:161]
	v_lshlrev_b64 v[162:163], 6, v[162:163]
	v_lshl_add_u64 v[162:163], s[24:25], 0, v[162:163]
	v_lshl_add_u64 v[170:171], v[162:163], 0, v[148:149]
	v_pk_mul_f32 v[162:163], v[44:45], v[128:129]
	s_mov_b64 s[12:13], 0xa0
	v_cvt_pk_bf16_f32 v162, v162, v163
	v_cvt_pk_bf16_f32 v163, v164, v165
	v_pk_mul_f32 v[164:165], v[40:41], v[132:133]
	s_nop 0
	v_cvt_pk_bf16_f32 v164, v164, v165
	v_cvt_pk_bf16_f32 v165, v198, v199
	global_store_dwordx4 v[170:171], v[162:165], off sc1
	v_pk_mul_f32 v[170:171], v[28:29], v[128:129]
	v_pk_mul_f32 v[128:129], v[12:13], v[128:129]
	v_lshl_add_u64 v[162:163], v[150:151], 0, s[12:13]
	v_lshl_add_u64 v[164:165], v[136:137], 0, v[162:163]
	v_cvt_pk_bf16_f32 v198, v170, v171
	v_pk_mul_f32 v[170:171], v[30:31], v[130:131]
	v_lshlrev_b64 v[164:165], 6, v[164:165]
	v_cvt_pk_bf16_f32 v199, v170, v171
	v_pk_mul_f32 v[170:171], v[24:25], v[132:133]
	v_lshl_add_u64 v[164:165], s[24:25], 0, v[164:165]
	v_cvt_pk_bf16_f32 v200, v170, v171
	v_pk_mul_f32 v[170:171], v[26:27], v[134:135]
	v_lshl_add_u64 v[164:165], v[164:165], 0, v[148:149]
	v_cvt_pk_bf16_f32 v201, v170, v171
	s_mov_b64 s[12:13], 0xb0
	global_store_dwordx4 v[164:165], v[198:201], off sc1
	v_lshl_add_u64 v[164:165], v[150:151], 0, s[12:13]
	v_lshl_add_u64 v[136:137], v[136:137], 0, v[164:165]
	v_lshlrev_b64 v[136:137], 6, v[136:137]
	v_pk_mul_f32 v[130:131], v[14:15], v[130:131]
	v_lshl_add_u64 v[136:137], s[24:25], 0, v[136:137]
	v_cvt_pk_bf16_f32 v128, v128, v129
	v_cvt_pk_bf16_f32 v129, v130, v131
	v_pk_mul_f32 v[130:131], v[8:9], v[132:133]
	v_pk_mul_f32 v[132:133], v[10:11], v[134:135]
	v_lshl_add_u64 v[136:137], v[136:137], 0, v[148:149]
	v_cvt_pk_bf16_f32 v130, v130, v131
	v_cvt_pk_bf16_f32 v131, v132, v133
	global_store_dwordx4 v[136:137], v[128:131], off sc1
	s_andn2_b64 vcc, exec, s[4:5]
	s_mov_b64 s[12:13], -1
	s_cbranch_vccnz .LBB0_975
	s_lshl_b32 s12, s83, 10
	s_add_i32 s12, s74, s12
	v_lshl_add_u32 v132, v166, 2, s12
	ds_read_b128 v[128:131], v132 offset:512
	ds_read_b128 v[132:135], v132 offset:528
	s_mov_b64 s[12:13], 0

.LBB0_977:
	v_add_u32_e32 v136, 0x80, v196
	v_ashrrev_i32_e32 v136, 5, v136
	v_ashrrev_i32_e32 v137, 31, v136
	v_lshlrev_b64 v[136:137], s58, v[136:137]
	v_lshl_add_u64 v[150:151], v[136:137], 0, v[150:151]
	v_lshlrev_b64 v[150:151], 6, v[150:151]
	s_waitcnt lgkmcnt(0)
	v_pk_mul_f32 v[166:167], v[116:117], v[128:129]
	v_pk_mul_f32 v[168:169], v[118:119], v[130:131]
	v_lshl_add_u64 v[150:151], s[24:25], 0, v[150:151]
	v_mov_b32_e32 v149, v139
	v_cvt_pk_bf16_f32 v166, v166, v167
	v_cvt_pk_bf16_f32 v167, v168, v169
	v_pk_mul_f32 v[168:169], v[112:113], v[132:133]
	v_pk_mul_f32 v[170:171], v[114:115], v[134:135]
	v_lshl_add_u64 v[150:151], v[150:151], 0, v[148:149]
	v_cvt_pk_bf16_f32 v168, v168, v169
	v_cvt_pk_bf16_f32 v169, v170, v171
	global_store_dwordx4 v[150:151], v[166:169], off sc1
	v_lshl_add_u64 v[150:151], v[136:137], 0, v[152:153]
	v_lshlrev_b64 v[150:151], 6, v[150:151]
	v_lshl_add_u64 v[150:151], s[24:25], 0, v[150:151]
	v_lshl_add_u64 v[166:167], v[150:151], 0, v[148:149]
	v_pk_mul_f32 v[150:151], v[100:101], v[128:129]
	v_pk_mul_f32 v[152:153], v[102:103], v[130:131]
	v_cvt_pk_bf16_f32 v150, v150, v151
	v_cvt_pk_bf16_f32 v151, v152, v153
	v_pk_mul_f32 v[152:153], v[96:97], v[132:133]
	v_pk_mul_f32 v[168:169], v[98:99], v[134:135]
	v_cvt_pk_bf16_f32 v152, v152, v153
	v_cvt_pk_bf16_f32 v153, v168, v169
	global_store_dwordx4 v[166:167], v[150:153], off sc1
	v_pk_mul_f32 v[166:167], v[82:83], v[134:135]
	s_nop 0
	v_lshl_add_u64 v[150:151], v[136:137], 0, v[154:155]
	v_lshlrev_b64 v[150:151], 6, v[150:151]
	v_lshl_add_u64 v[150:151], s[24:25], 0, v[150:151]
	v_lshl_add_u64 v[154:155], v[150:151], 0, v[148:149]
	v_pk_mul_f32 v[150:151], v[84:85], v[128:129]
	v_pk_mul_f32 v[152:153], v[86:87], v[130:131]
	v_cvt_pk_bf16_f32 v150, v150, v151
	v_cvt_pk_bf16_f32 v151, v152, v153
	v_pk_mul_f32 v[152:153], v[80:81], v[132:133]
	s_nop 0
	v_cvt_pk_bf16_f32 v152, v152, v153
	v_cvt_pk_bf16_f32 v153, v166, v167
	global_store_dwordx4 v[154:155], v[150:153], off sc1
	s_nop 1
	v_lshl_add_u64 v[150:151], v[136:137], 0, v[156:157]
	v_lshlrev_b64 v[150:151], 6, v[150:151]
	v_lshl_add_u64 v[150:151], s[24:25], 0, v[150:151]
	v_lshl_add_u64 v[154:155], v[150:151], 0, v[148:149]
	v_pk_mul_f32 v[150:151], v[68:69], v[128:129]
	v_pk_mul_f32 v[152:153], v[70:71], v[130:131]
	v_cvt_pk_bf16_f32 v150, v150, v151
	v_cvt_pk_bf16_f32 v151, v152, v153
	v_pk_mul_f32 v[152:153], v[64:65], v[132:133]
	v_pk_mul_f32 v[156:157], v[66:67], v[134:135]
	v_cvt_pk_bf16_f32 v152, v152, v153
	v_cvt_pk_bf16_f32 v153, v156, v157
	global_store_dwordx4 v[154:155], v[150:153], off sc1
	v_pk_mul_f32 v[156:157], v[50:51], v[134:135]
	s_nop 0
	v_lshl_add_u64 v[150:151], v[136:137], 0, v[158:159]
	v_lshlrev_b64 v[150:151], 6, v[150:151]
	v_lshl_add_u64 v[150:151], s[24:25], 0, v[150:151]
	v_lshl_add_u64 v[154:155], v[150:151], 0, v[148:149]
	v_pk_mul_f32 v[150:151], v[52:53], v[128:129]
	v_pk_mul_f32 v[152:153], v[54:55], v[130:131]
	v_cvt_pk_bf16_f32 v150, v150, v151
	v_cvt_pk_bf16_f32 v151, v152, v153
	v_pk_mul_f32 v[152:153], v[48:49], v[132:133]
	s_nop 0
	v_cvt_pk_bf16_f32 v152, v152, v153
	v_cvt_pk_bf16_f32 v153, v156, v157
	global_store_dwordx4 v[154:155], v[150:153], off sc1
	v_pk_mul_f32 v[156:157], v[34:35], v[134:135]
	s_nop 0
	v_lshl_add_u64 v[150:151], v[136:137], 0, v[160:161]
	v_lshlrev_b64 v[150:151], 6, v[150:151]
	v_lshl_add_u64 v[150:151], s[24:25], 0, v[150:151]
	v_lshl_add_u64 v[154:155], v[150:151], 0, v[148:149]
	v_pk_mul_f32 v[150:151], v[36:37], v[128:129]
	v_pk_mul_f32 v[152:153], v[38:39], v[130:131]
	v_cvt_pk_bf16_f32 v150, v150, v151
	v_cvt_pk_bf16_f32 v151, v152, v153
	v_pk_mul_f32 v[152:153], v[32:33], v[132:133]
	s_nop 0
	v_cvt_pk_bf16_f32 v152, v152, v153
	v_cvt_pk_bf16_f32 v153, v156, v157
	global_store_dwordx4 v[154:155], v[150:153], off sc1
	v_pk_mul_f32 v[156:157], v[18:19], v[134:135]
	s_nop 0
	v_lshl_add_u64 v[150:151], v[136:137], 0, v[162:163]
	v_lshlrev_b64 v[150:151], 6, v[150:151]
	v_lshl_add_u64 v[150:151], s[24:25], 0, v[150:151]
	v_lshl_add_u64 v[136:137], v[136:137], 0, v[164:165]
	v_lshl_add_u64 v[154:155], v[150:151], 0, v[148:149]
	v_pk_mul_f32 v[150:151], v[20:21], v[128:129]
	v_pk_mul_f32 v[152:153], v[22:23], v[130:131]
	v_lshlrev_b64 v[136:137], 6, v[136:137]
	v_pk_mul_f32 v[128:129], v[4:5], v[128:129]
	v_pk_mul_f32 v[130:131], v[6:7], v[130:131]
	v_cvt_pk_bf16_f32 v150, v150, v151
	v_cvt_pk_bf16_f32 v151, v152, v153
	v_pk_mul_f32 v[152:153], v[16:17], v[132:133]
	v_lshl_add_u64 v[136:137], s[24:25], 0, v[136:137]
	v_cvt_pk_bf16_f32 v128, v128, v129
	v_cvt_pk_bf16_f32 v129, v130, v131
	v_pk_mul_f32 v[130:131], v[0:1], v[132:133]
	v_pk_mul_f32 v[132:133], v[2:3], v[134:135]
	v_cvt_pk_bf16_f32 v152, v152, v153
	v_cvt_pk_bf16_f32 v153, v156, v157
	v_lshl_add_u64 v[136:137], v[136:137], 0, v[148:149]
	v_cvt_pk_bf16_f32 v130, v130, v131
	v_cvt_pk_bf16_f32 v131, v132, v133
	global_store_dwordx4 v[154:155], v[150:153], off sc1
	global_store_dwordx4 v[136:137], v[128:131], off sc1
	s_branch .LBB0_1044

.LBB0_986:
	s_waitcnt lgkmcnt(0)
	v_pk_mul_f32 v[126:127], v[126:127], v[134:135] op_sel_hi:[1,0]
	v_pk_mul_f32 v[124:125], v[124:125], v[134:135] op_sel_hi:[1,0]
	v_pk_mul_f32 v[148:149], v[122:123], v[134:135] op_sel_hi:[1,0]
	v_pk_mul_f32 v[122:123], v[120:121], v[134:135] op_sel_hi:[1,0]
	v_cvt_pk_bf16_f32 v120, v124, v125
	v_cvt_pk_bf16_f32 v121, v126, v127
	v_cvt_pk_bf16_f32 v122, v122, v123
	v_cvt_pk_bf16_f32 v123, v148, v149
	global_store_dwordx4 v[136:137], v[120:123], off sc1
	v_pk_mul_f32 v[118:119], v[118:119], v[134:135] op_sel_hi:[1,0]
	v_pk_mul_f32 v[116:117], v[116:117], v[134:135] op_sel_hi:[1,0]
	v_pk_mul_f32 v[120:121], v[114:115], v[134:135] op_sel_hi:[1,0]
	v_pk_mul_f32 v[114:115], v[112:113], v[134:135] op_sel_hi:[1,0]
	s_lshl_b32 s56, s14, 1
	v_cvt_pk_bf16_f32 v112, v116, v117
	v_cvt_pk_bf16_f32 v113, v118, v119
	v_cvt_pk_bf16_f32 v114, v114, v115
	v_cvt_pk_bf16_f32 v115, v120, v121
	v_lshl_add_u64 v[116:117], v[136:137], 0, s[56:57]
	s_and_b64 vcc, exec, s[40:41]
	s_mov_b64 s[14:15], -1
	global_store_dwordx4 v[116:117], v[112:115], off sc1
	s_cbranch_vccnz .LBB0_988
	s_lshl_b32 s14, s83, 10
	s_add_i32 s14, s75, s14
	v_lshl_add_u32 v112, v135, 2, s14
	ds_read_b32 v112, v112 offset:64
	s_mov_b64 s[14:15], 0

.LBB0_994:
	s_waitcnt lgkmcnt(0)
	v_pk_mul_f32 v[110:111], v[110:111], v[112:113] op_sel_hi:[1,0]
	v_pk_mul_f32 v[108:109], v[108:109], v[112:113] op_sel_hi:[1,0]
	v_pk_mul_f32 v[114:115], v[106:107], v[112:113] op_sel_hi:[1,0]
	v_pk_mul_f32 v[106:107], v[104:105], v[112:113] op_sel_hi:[1,0]
	v_cvt_pk_bf16_f32 v104, v108, v109
	v_cvt_pk_bf16_f32 v105, v110, v111
	v_cvt_pk_bf16_f32 v106, v106, v107
	v_cvt_pk_bf16_f32 v107, v114, v115
	global_store_dwordx4 v[116:117], v[104:107], off sc1
	v_pk_mul_f32 v[102:103], v[102:103], v[112:113] op_sel_hi:[1,0]
	v_pk_mul_f32 v[100:101], v[100:101], v[112:113] op_sel_hi:[1,0]
	v_pk_mul_f32 v[104:105], v[98:99], v[112:113] op_sel_hi:[1,0]
	v_pk_mul_f32 v[98:99], v[96:97], v[112:113] op_sel_hi:[1,0]
	s_lshl_b32 s56, s12, 1
	v_cvt_pk_bf16_f32 v96, v100, v101
	v_cvt_pk_bf16_f32 v97, v102, v103
	v_cvt_pk_bf16_f32 v98, v98, v99
	v_cvt_pk_bf16_f32 v99, v104, v105
	v_lshl_add_u64 v[100:101], v[116:117], 0, s[56:57]
	s_and_b64 vcc, exec, s[40:41]
	s_mov_b64 s[12:13], -1
	global_store_dwordx4 v[100:101], v[96:99], off sc1
	s_cbranch_vccnz .LBB0_998
	s_lshl_b32 s12, s83, 10
	s_add_i32 s12, s75, s12
	v_lshl_add_u32 v96, v135, 2, s12
	ds_read_b32 v96, v96 offset:128
	v_or_b32_e32 v100, 32, v128
	v_ashrrev_i32_e32 v101, 31, v100
	s_cbranch_execz .LBB0_999

.LBB0_1002:
	s_waitcnt lgkmcnt(0)
	v_pk_mul_f32 v[94:95], v[94:95], v[96:97] op_sel_hi:[1,0]
	v_pk_mul_f32 v[92:93], v[92:93], v[96:97] op_sel_hi:[1,0]
	v_pk_mul_f32 v[100:101], v[90:91], v[96:97] op_sel_hi:[1,0]
	v_pk_mul_f32 v[90:91], v[88:89], v[96:97] op_sel_hi:[1,0]
	v_cvt_pk_bf16_f32 v88, v92, v93
	v_cvt_pk_bf16_f32 v89, v94, v95
	v_cvt_pk_bf16_f32 v90, v90, v91
	v_cvt_pk_bf16_f32 v91, v100, v101
	global_store_dwordx4 v[98:99], v[88:91], off sc1
	v_pk_mul_f32 v[86:87], v[86:87], v[96:97] op_sel_hi:[1,0]
	v_pk_mul_f32 v[84:85], v[84:85], v[96:97] op_sel_hi:[1,0]
	v_pk_mul_f32 v[88:89], v[82:83], v[96:97] op_sel_hi:[1,0]
	v_pk_mul_f32 v[82:83], v[80:81], v[96:97] op_sel_hi:[1,0]
	s_lshl_b32 s56, s12, 1
	v_cvt_pk_bf16_f32 v80, v84, v85
	v_cvt_pk_bf16_f32 v81, v86, v87
	v_cvt_pk_bf16_f32 v82, v82, v83
	v_cvt_pk_bf16_f32 v83, v88, v89
	v_lshl_add_u64 v[84:85], v[98:99], 0, s[56:57]
	s_and_b64 vcc, exec, s[40:41]
	s_mov_b64 s[12:13], -1
	global_store_dwordx4 v[84:85], v[80:83], off sc1
	s_cbranch_vccnz .LBB0_1006
	s_lshl_b32 s12, s83, 10
	s_add_i32 s12, s75, s12
	v_lshl_add_u32 v80, v135, 2, s12
	ds_read_b32 v80, v80 offset:192
	v_or_b32_e32 v84, 48, v128
	v_ashrrev_i32_e32 v85, 31, v84
	s_cbranch_execz .LBB0_1007

.LBB0_1010:
	s_waitcnt lgkmcnt(0)
	v_pk_mul_f32 v[78:79], v[78:79], v[80:81] op_sel_hi:[1,0]
	v_pk_mul_f32 v[76:77], v[76:77], v[80:81] op_sel_hi:[1,0]
	v_pk_mul_f32 v[84:85], v[74:75], v[80:81] op_sel_hi:[1,0]
	v_pk_mul_f32 v[74:75], v[72:73], v[80:81] op_sel_hi:[1,0]
	v_cvt_pk_bf16_f32 v72, v76, v77
	v_cvt_pk_bf16_f32 v73, v78, v79
	v_cvt_pk_bf16_f32 v74, v74, v75
	v_cvt_pk_bf16_f32 v75, v84, v85
	global_store_dwordx4 v[82:83], v[72:75], off sc1
	v_pk_mul_f32 v[70:71], v[70:71], v[80:81] op_sel_hi:[1,0]
	v_pk_mul_f32 v[68:69], v[68:69], v[80:81] op_sel_hi:[1,0]
	v_pk_mul_f32 v[72:73], v[66:67], v[80:81] op_sel_hi:[1,0]
	v_pk_mul_f32 v[66:67], v[64:65], v[80:81] op_sel_hi:[1,0]
	s_lshl_b32 s56, s12, 1
	v_cvt_pk_bf16_f32 v64, v68, v69
	v_cvt_pk_bf16_f32 v65, v70, v71
	v_cvt_pk_bf16_f32 v66, v66, v67
	v_cvt_pk_bf16_f32 v67, v72, v73
	v_lshl_add_u64 v[68:69], v[82:83], 0, s[56:57]
	s_and_b64 vcc, exec, s[40:41]
	s_mov_b64 s[12:13], -1
	global_store_dwordx4 v[68:69], v[64:67], off sc1
	s_cbranch_vccnz .LBB0_1014
	s_lshl_b32 s12, s83, 10
	s_add_i32 s12, s75, s12
	v_lshl_add_u32 v64, v135, 2, s12
	ds_read_b32 v64, v64 offset:512
	v_add_u32_e32 v68, 0x80, v128
	v_ashrrev_i32_e32 v69, 31, v68
	s_cbranch_execz .LBB0_1015

.LBB0_1018:
	s_waitcnt lgkmcnt(0)
	v_pk_mul_f32 v[62:63], v[62:63], v[64:65] op_sel_hi:[1,0]
	v_pk_mul_f32 v[60:61], v[60:61], v[64:65] op_sel_hi:[1,0]
	v_pk_mul_f32 v[68:69], v[58:59], v[64:65] op_sel_hi:[1,0]
	v_pk_mul_f32 v[58:59], v[56:57], v[64:65] op_sel_hi:[1,0]
	v_cvt_pk_bf16_f32 v56, v60, v61
	v_cvt_pk_bf16_f32 v57, v62, v63
	v_cvt_pk_bf16_f32 v58, v58, v59
	v_cvt_pk_bf16_f32 v59, v68, v69
	global_store_dwordx4 v[66:67], v[56:59], off sc1
	v_pk_mul_f32 v[54:55], v[54:55], v[64:65] op_sel_hi:[1,0]
	v_pk_mul_f32 v[52:53], v[52:53], v[64:65] op_sel_hi:[1,0]
	v_pk_mul_f32 v[56:57], v[50:51], v[64:65] op_sel_hi:[1,0]
	v_pk_mul_f32 v[50:51], v[48:49], v[64:65] op_sel_hi:[1,0]
	s_lshl_b32 s56, s12, 1
	v_cvt_pk_bf16_f32 v48, v52, v53
	v_cvt_pk_bf16_f32 v49, v54, v55
	v_cvt_pk_bf16_f32 v50, v50, v51
	v_cvt_pk_bf16_f32 v51, v56, v57
	v_lshl_add_u64 v[52:53], v[66:67], 0, s[56:57]
	s_and_b64 vcc, exec, s[40:41]
	s_mov_b64 s[12:13], -1
	global_store_dwordx4 v[52:53], v[48:51], off sc1
	s_cbranch_vccnz .LBB0_1022
	s_lshl_b32 s12, s83, 10
	s_add_i32 s12, s75, s12
	v_lshl_add_u32 v48, v135, 2, s12
	ds_read_b32 v48, v48 offset:576
	v_add_u32_e32 v52, 0x90, v128
	v_ashrrev_i32_e32 v53, 31, v52
	s_cbranch_execz .LBB0_1023

.LBB0_1026:
	s_waitcnt lgkmcnt(0)
	v_pk_mul_f32 v[46:47], v[46:47], v[48:49] op_sel_hi:[1,0]
	v_pk_mul_f32 v[44:45], v[44:45], v[48:49] op_sel_hi:[1,0]
	v_pk_mul_f32 v[52:53], v[42:43], v[48:49] op_sel_hi:[1,0]
	v_pk_mul_f32 v[42:43], v[40:41], v[48:49] op_sel_hi:[1,0]
	v_cvt_pk_bf16_f32 v40, v44, v45
	v_cvt_pk_bf16_f32 v41, v46, v47
	v_cvt_pk_bf16_f32 v42, v42, v43
	v_cvt_pk_bf16_f32 v43, v52, v53
	global_store_dwordx4 v[50:51], v[40:43], off sc1
	v_pk_mul_f32 v[38:39], v[38:39], v[48:49] op_sel_hi:[1,0]
	v_pk_mul_f32 v[36:37], v[36:37], v[48:49] op_sel_hi:[1,0]
	v_pk_mul_f32 v[40:41], v[34:35], v[48:49] op_sel_hi:[1,0]
	v_pk_mul_f32 v[34:35], v[32:33], v[48:49] op_sel_hi:[1,0]
	s_lshl_b32 s56, s12, 1
	v_cvt_pk_bf16_f32 v32, v36, v37
	v_cvt_pk_bf16_f32 v33, v38, v39
	v_cvt_pk_bf16_f32 v34, v34, v35
	v_cvt_pk_bf16_f32 v35, v40, v41
	v_lshl_add_u64 v[36:37], v[50:51], 0, s[56:57]
	s_and_b64 vcc, exec, s[40:41]
	s_mov_b64 s[12:13], -1
	global_store_dwordx4 v[36:37], v[32:35], off sc1
	s_cbranch_vccnz .LBB0_1030
	s_lshl_b32 s12, s83, 10
	s_add_i32 s12, s75, s12
	v_lshl_add_u32 v32, v135, 2, s12
	ds_read_b32 v32, v32 offset:640
	v_add_u32_e32 v36, 0xa0, v128
	v_ashrrev_i32_e32 v37, 31, v36
	s_cbranch_execz .LBB0_1031

.LBB0_1034:
	s_waitcnt lgkmcnt(0)
	v_pk_mul_f32 v[30:31], v[30:31], v[32:33] op_sel_hi:[1,0]
	v_pk_mul_f32 v[28:29], v[28:29], v[32:33] op_sel_hi:[1,0]
	v_pk_mul_f32 v[36:37], v[26:27], v[32:33] op_sel_hi:[1,0]
	v_pk_mul_f32 v[26:27], v[24:25], v[32:33] op_sel_hi:[1,0]
	v_cvt_pk_bf16_f32 v24, v28, v29
	v_cvt_pk_bf16_f32 v25, v30, v31
	v_cvt_pk_bf16_f32 v26, v26, v27
	v_cvt_pk_bf16_f32 v27, v36, v37
	global_store_dwordx4 v[34:35], v[24:27], off sc1
	v_pk_mul_f32 v[22:23], v[22:23], v[32:33] op_sel_hi:[1,0]
	v_pk_mul_f32 v[20:21], v[20:21], v[32:33] op_sel_hi:[1,0]
	v_pk_mul_f32 v[24:25], v[18:19], v[32:33] op_sel_hi:[1,0]
	v_pk_mul_f32 v[18:19], v[16:17], v[32:33] op_sel_hi:[1,0]
	s_lshl_b32 s56, s12, 1
	v_cvt_pk_bf16_f32 v16, v20, v21
	v_cvt_pk_bf16_f32 v17, v22, v23
	v_cvt_pk_bf16_f32 v18, v18, v19
	v_cvt_pk_bf16_f32 v19, v24, v25
	v_lshl_add_u64 v[20:21], v[34:35], 0, s[56:57]
	s_and_b64 vcc, exec, s[40:41]
	s_mov_b64 s[12:13], -1
	global_store_dwordx4 v[20:21], v[16:19], off sc1
	s_cbranch_vccnz .LBB0_1038
	s_lshl_b32 s12, s83, 10
	s_add_i32 s12, s75, s12
	v_lshl_add_u32 v16, v135, 2, s12
	ds_read_b32 v16, v16 offset:704
	v_add_u32_e32 v20, 0xb0, v128
	v_ashrrev_i32_e32 v21, 31, v20
	s_cbranch_execz .LBB0_1039

.LBB0_1042:
	s_waitcnt lgkmcnt(0)
	v_pk_mul_f32 v[14:15], v[14:15], v[16:17] op_sel_hi:[1,0]
	v_pk_mul_f32 v[12:13], v[12:13], v[16:17] op_sel_hi:[1,0]
	v_pk_mul_f32 v[20:21], v[10:11], v[16:17] op_sel_hi:[1,0]
	v_pk_mul_f32 v[10:11], v[8:9], v[16:17] op_sel_hi:[1,0]
	v_cvt_pk_bf16_f32 v8, v12, v13
	v_cvt_pk_bf16_f32 v9, v14, v15
	v_cvt_pk_bf16_f32 v10, v10, v11
	v_cvt_pk_bf16_f32 v11, v20, v21
	global_store_dwordx4 v[18:19], v[8:11], off sc1
	v_pk_mul_f32 v[6:7], v[6:7], v[16:17] op_sel_hi:[1,0]
	v_pk_mul_f32 v[4:5], v[4:5], v[16:17] op_sel_hi:[1,0]
	v_pk_mul_f32 v[8:9], v[2:3], v[16:17] op_sel_hi:[1,0]
	v_pk_mul_f32 v[2:3], v[0:1], v[16:17] op_sel_hi:[1,0]
	s_lshl_b32 s56, s12, 1
	v_cvt_pk_bf16_f32 v0, v4, v5
	v_cvt_pk_bf16_f32 v1, v6, v7
	v_cvt_pk_bf16_f32 v2, v2, v3
	v_cvt_pk_bf16_f32 v3, v8, v9
	v_lshl_add_u64 v[4:5], v[18:19], 0, s[56:57]
	global_store_dwordx4 v[4:5], v[0:3], off sc1
	s_andn2_b64 vcc, exec, s[38:39]
	s_mov_b64 s[12:13], -1
	s_cbranch_vccnz .LBB0_959
	s_branch .LBB0_1045
